# DA unit epilogue: 128 global_store_short per wave replaced by LDS transpose (ds_write_b64 + ds_read_b64_tr_b16) and 16 global_store_dwordx4
# speedup vs baseline: 1.0026x; 1.0025x over previous
; __device__ __forceinline__ unsigned cvtpk(float lo, float hi) { f32x2_t v = {lo, hi}; bf16x2_t b = __builtin_convertvector(v, bf16x2_t); return __builtin_bit_cast(unsigned, b); }
; #define OPQ(x) ({ int t_ = (x); asm volatile("" : "+v"(t_)); t_; })
; #define lane mk_lane()
; __device__ __forceinline__ void attn_unit_da(const AttnUnit& U, char* lds) {
;     ...
;   if (hi == 0) li_l[r32] = l_reg; asm volatile("s_waitcnt lgkmcnt(0)" ::: "memory");
;   { const int le_ = OPQ(lane); const int obase = (wid * QBLK + 4 * (le_ >> 5)) * U.ldo + (le_ & 31);
; #pragma unroll
;     for (int r = 0; r < 16; ++r) { const int orl = (r & 3) + 8 * (r >> 2); const float rl = __builtin_amdgcn_rcpf(li_l[orl + 4 * hi]); const int ooff = obase + orl * U.ldo;
; #pragma unroll
;       for (int d0 = 0; d0 < 8; ++d0) U.O[ooff + d0 * 32] = (bf16_t)(cvtpk(o[d0][r] * rl, 0.f) & 0xffffu); } }
.LBB0_1904:
	s_or_b64 exec, exec, s[0:1]
	v_add_u32_e32 v0, s24, v239
	s_waitcnt lgkmcnt(0)
	ds_read_b128 v[132:135], v0
	ds_read_b128 v[136:139], v0 offset:32
	ds_read_b128 v[140:143], v0 offset:64
	ds_read_b128 v[144:147], v0 offset:96
	s_lshl_b32 s0, s66, 13
	s_add_u32 s2, s52, s0
	s_addc_u32 s3, s53, 0
	s_lshl_b32 s0, s65, 9
	s_ashr_i32 s1, s0, 31
	s_lshl_b64 s[0:1], s[0:1], 1
	s_add_u32 s0, s2, s0
	s_addc_u32 s1, s3, s1
	s_lshl_b32 s2, s64, 9
	s_add_u32 s0, s0, s2
	s_addc_u32 s1, s1, 0
	v_and_b32_e32 v130, 31, v243
	v_lshrrev_b32_e32 v131, 5, v243
	v_lshlrev_b32_e32 v148, 6, v130
	v_lshl_add_u32 v148, v131, 3, v148
	s_lshl_b32 s2, s69, 12
	s_add_i32 s2, s2, 0x8000
	v_add_u32_e32 v148, s2, v148
	v_lshrrev_b32_e32 v130, 5, v243
	v_lshlrev_b32_e32 v149, 9, v130
	v_bfe_u32 v130, v243, 2, 2
	v_lshl_add_u32 v149, v130, 6, v149
	v_bfe_u32 v130, v243, 4, 1
	v_lshl_add_u32 v149, v130, 5, v149
	v_and_b32_e32 v131, 3, v243
	v_lshl_add_u32 v149, v131, 3, v149
	v_add_u32_e32 v149, s2, v149
	v_and_b32_e32 v131, 15, v243
	v_lshl_add_u32 v131, v130, 4, v131
	v_add_u32_e32 v131, s63, v131
	v_lshrrev_b32_e32 v130, 5, v243
	v_lshlrev_b32_e32 v130, 3, v130
	v_lshl_or_b32 v130, v131, 12, v130
	v_ashrrev_i32_e32 v131, 31, v130
	v_lshl_add_u64 v[150:151], v[130:131], 1, s[0:1]
	s_waitcnt lgkmcnt(0)
	v_rcp_f32_e32 v132, v132
	v_rcp_f32_e32 v133, v133
	v_rcp_f32_e32 v134, v134
	v_rcp_f32_e32 v135, v135
	v_rcp_f32_e32 v136, v136
	v_rcp_f32_e32 v137, v137
	v_rcp_f32_e32 v138, v138
	v_rcp_f32_e32 v139, v139
	v_rcp_f32_e32 v140, v140
	v_rcp_f32_e32 v141, v141
	v_rcp_f32_e32 v142, v142
	v_rcp_f32_e32 v143, v143
	v_rcp_f32_e32 v144, v144
	v_rcp_f32_e32 v145, v145
	v_rcp_f32_e32 v146, v146
	v_rcp_f32_e32 v147, v147
	v_mul_f32_e32 v114, v114, v132
	v_mul_f32_e32 v115, v115, v133
	v_mul_f32_e32 v116, v116, v134
	v_mul_f32_e32 v117, v117, v135
	v_cvt_pk_bf16_f32 v152, v114, v115
	v_cvt_pk_bf16_f32 v153, v116, v117
	ds_write_b64 v148, v[152:153]
	v_mul_f32_e32 v118, v118, v136
	v_mul_f32_e32 v119, v119, v137
	v_mul_f32_e32 v120, v120, v138
	v_mul_f32_e32 v121, v121, v139
	v_cvt_pk_bf16_f32 v154, v118, v119
	v_cvt_pk_bf16_f32 v155, v120, v121
	ds_write_b64 v148, v[154:155] offset:16
	v_mul_f32_e32 v122, v122, v140
	v_mul_f32_e32 v123, v123, v141
	v_mul_f32_e32 v124, v124, v142
	v_mul_f32_e32 v125, v125, v143
	v_cvt_pk_bf16_f32 v156, v122, v123
	v_cvt_pk_bf16_f32 v157, v124, v125
	ds_write_b64 v148, v[156:157] offset:32
	v_mul_f32_e32 v126, v126, v144
	v_mul_f32_e32 v127, v127, v145
	v_mul_f32_e32 v128, v128, v146
	v_mul_f32_e32 v129, v129, v147
	v_cvt_pk_bf16_f32 v158, v126, v127
	v_cvt_pk_bf16_f32 v159, v128, v129
	ds_write_b64 v148, v[158:159] offset:48
	v_mul_f32_e32 v98, v98, v132
	v_mul_f32_e32 v99, v99, v133
	v_mul_f32_e32 v100, v100, v134
	v_mul_f32_e32 v101, v101, v135
	v_cvt_pk_bf16_f32 v152, v98, v99
	v_cvt_pk_bf16_f32 v153, v100, v101
	ds_write_b64 v148, v[152:153] offset:2048
	v_mul_f32_e32 v102, v102, v136
	v_mul_f32_e32 v103, v103, v137
	v_mul_f32_e32 v104, v104, v138
	v_mul_f32_e32 v105, v105, v139
	v_cvt_pk_bf16_f32 v154, v102, v103
	v_cvt_pk_bf16_f32 v155, v104, v105
	ds_write_b64 v148, v[154:155] offset:2064
	v_mul_f32_e32 v106, v106, v140
	v_mul_f32_e32 v107, v107, v141
	v_mul_f32_e32 v108, v108, v142
	v_mul_f32_e32 v109, v109, v143
	v_cvt_pk_bf16_f32 v156, v106, v107
	v_cvt_pk_bf16_f32 v157, v108, v109
	ds_write_b64 v148, v[156:157] offset:2080
	v_mul_f32_e32 v110, v110, v144
	v_mul_f32_e32 v111, v111, v145
	v_mul_f32_e32 v112, v112, v146
	v_mul_f32_e32 v113, v113, v147
	v_cvt_pk_bf16_f32 v158, v110, v111
	v_cvt_pk_bf16_f32 v159, v112, v113
	ds_write_b64 v148, v[158:159] offset:2096
	s_waitcnt lgkmcnt(0)
	ds_read_b64_tr_b16 v[160:161], v149
	ds_read_b64_tr_b16 v[162:163], v149 offset:256
	ds_read_b64_tr_b16 v[164:165], v149 offset:1024
	ds_read_b64_tr_b16 v[166:167], v149 offset:1280
	ds_read_b64_tr_b16 v[168:169], v149 offset:2048
	ds_read_b64_tr_b16 v[170:171], v149 offset:2304
	ds_read_b64_tr_b16 v[172:173], v149 offset:3072
	ds_read_b64_tr_b16 v[174:175], v149 offset:3328
	s_waitcnt lgkmcnt(0)
	global_store_dwordx4 v[150:151], v[160:163], off
	global_store_dwordx4 v[150:151], v[164:167], off offset:32
	global_store_dwordx4 v[150:151], v[168:171], off offset:64
	global_store_dwordx4 v[150:151], v[172:175], off offset:96
	s_nop 1
	v_mul_f32_e32 v82, v82, v132
	v_mul_f32_e32 v83, v83, v133
	v_mul_f32_e32 v84, v84, v134
	v_mul_f32_e32 v85, v85, v135
	v_cvt_pk_bf16_f32 v152, v82, v83
	v_cvt_pk_bf16_f32 v153, v84, v85
	ds_write_b64 v148, v[152:153]
	v_mul_f32_e32 v86, v86, v136
	v_mul_f32_e32 v87, v87, v137
	v_mul_f32_e32 v88, v88, v138
	v_mul_f32_e32 v89, v89, v139
	v_cvt_pk_bf16_f32 v154, v86, v87
	v_cvt_pk_bf16_f32 v155, v88, v89
	ds_write_b64 v148, v[154:155] offset:16
	v_mul_f32_e32 v90, v90, v140
	v_mul_f32_e32 v91, v91, v141
	v_mul_f32_e32 v92, v92, v142
	v_mul_f32_e32 v93, v93, v143
	v_cvt_pk_bf16_f32 v156, v90, v91
	v_cvt_pk_bf16_f32 v157, v92, v93
	ds_write_b64 v148, v[156:157] offset:32
	v_mul_f32_e32 v94, v94, v144
	v_mul_f32_e32 v95, v95, v145
	v_mul_f32_e32 v96, v96, v146
	v_mul_f32_e32 v97, v97, v147
	v_cvt_pk_bf16_f32 v158, v94, v95
	v_cvt_pk_bf16_f32 v159, v96, v97
	ds_write_b64 v148, v[158:159] offset:48
	v_mul_f32_e32 v66, v66, v132
	v_mul_f32_e32 v67, v67, v133
	v_mul_f32_e32 v68, v68, v134
	v_mul_f32_e32 v69, v69, v135
	v_cvt_pk_bf16_f32 v152, v66, v67
	v_cvt_pk_bf16_f32 v153, v68, v69
	ds_write_b64 v148, v[152:153] offset:2048
	v_mul_f32_e32 v70, v70, v136
	v_mul_f32_e32 v71, v71, v137
	v_mul_f32_e32 v72, v72, v138
	v_mul_f32_e32 v73, v73, v139
	v_cvt_pk_bf16_f32 v154, v70, v71
	v_cvt_pk_bf16_f32 v155, v72, v73
	ds_write_b64 v148, v[154:155] offset:2064
	v_mul_f32_e32 v74, v74, v140
	v_mul_f32_e32 v75, v75, v141
	v_mul_f32_e32 v76, v76, v142
	v_mul_f32_e32 v77, v77, v143
	v_cvt_pk_bf16_f32 v156, v74, v75
	v_cvt_pk_bf16_f32 v157, v76, v77
	ds_write_b64 v148, v[156:157] offset:2080
	v_mul_f32_e32 v78, v78, v144
	v_mul_f32_e32 v79, v79, v145
	v_mul_f32_e32 v80, v80, v146
	v_mul_f32_e32 v81, v81, v147
	v_cvt_pk_bf16_f32 v158, v78, v79
	v_cvt_pk_bf16_f32 v159, v80, v81
	ds_write_b64 v148, v[158:159] offset:2096
	s_waitcnt lgkmcnt(0)
; __device__ __forceinline__ unsigned cvtpk(float lo, float hi) { f32x2_t v = {lo, hi}; bf16x2_t b = __builtin_convertvector(v, bf16x2_t); return __builtin_bit_cast(unsigned, b); }
; #define OPQ(x) ({ int t_ = (x); asm volatile("" : "+v"(t_)); t_; })
; #define lane mk_lane()
; __device__ __forceinline__ void attn_unit_da(const AttnUnit& U, char* lds) {
;     ...
;   if (hi == 0) li_l[r32] = l_reg; asm volatile("s_waitcnt lgkmcnt(0)" ::: "memory");
;   { const int le_ = OPQ(lane); const int obase = (wid * QBLK + 4 * (le_ >> 5)) * U.ldo + (le_ & 31);
; #pragma unroll
;     for (int r = 0; r < 16; ++r) { const int orl = (r & 3) + 8 * (r >> 2); const float rl = __builtin_amdgcn_rcpf(li_l[orl + 4 * hi]); const int ooff = obase + orl * U.ldo;
; #pragma unroll
;       for (int d0 = 0; d0 < 8; ++d0) U.O[ooff + d0 * 32] = (bf16_t)(cvtpk(o[d0][r] * rl, 0.f) & 0xffffu); } }
; __global__ void __launch_bounds__(512, 2) fwd_kernel(Params p) {
;     ...
;         for (int it = vcu; it < 2048; it += G) {
	ds_read_b64_tr_b16 v[160:161], v149
	ds_read_b64_tr_b16 v[162:163], v149 offset:256
	ds_read_b64_tr_b16 v[164:165], v149 offset:1024
	ds_read_b64_tr_b16 v[166:167], v149 offset:1280
	ds_read_b64_tr_b16 v[168:169], v149 offset:2048
	ds_read_b64_tr_b16 v[170:171], v149 offset:2304
	ds_read_b64_tr_b16 v[172:173], v149 offset:3072
	ds_read_b64_tr_b16 v[174:175], v149 offset:3328
	s_waitcnt lgkmcnt(0)
	global_store_dwordx4 v[150:151], v[160:163], off offset:128
	global_store_dwordx4 v[150:151], v[164:167], off offset:160
	global_store_dwordx4 v[150:151], v[168:171], off offset:192
	global_store_dwordx4 v[150:151], v[172:175], off offset:224
	s_nop 1
	v_mul_f32_e32 v50, v50, v132
	v_mul_f32_e32 v51, v51, v133
	v_mul_f32_e32 v52, v52, v134
	v_mul_f32_e32 v53, v53, v135
	v_cvt_pk_bf16_f32 v152, v50, v51
	v_cvt_pk_bf16_f32 v153, v52, v53
	ds_write_b64 v148, v[152:153]
	v_mul_f32_e32 v54, v54, v136
	v_mul_f32_e32 v55, v55, v137
	v_mul_f32_e32 v56, v56, v138
	v_mul_f32_e32 v57, v57, v139
	v_cvt_pk_bf16_f32 v154, v54, v55
	v_cvt_pk_bf16_f32 v155, v56, v57
	ds_write_b64 v148, v[154:155] offset:16
	v_mul_f32_e32 v58, v58, v140
	v_mul_f32_e32 v59, v59, v141
	v_mul_f32_e32 v60, v60, v142
	v_mul_f32_e32 v61, v61, v143
	v_cvt_pk_bf16_f32 v156, v58, v59
	v_cvt_pk_bf16_f32 v157, v60, v61
	ds_write_b64 v148, v[156:157] offset:32
	v_mul_f32_e32 v62, v62, v144
	v_mul_f32_e32 v63, v63, v145
	v_mul_f32_e32 v64, v64, v146
	v_mul_f32_e32 v65, v65, v147
	v_cvt_pk_bf16_f32 v158, v62, v63
	v_cvt_pk_bf16_f32 v159, v64, v65
	ds_write_b64 v148, v[158:159] offset:48
	v_mul_f32_e32 v34, v34, v132
	v_mul_f32_e32 v35, v35, v133
	v_mul_f32_e32 v36, v36, v134
	v_mul_f32_e32 v37, v37, v135
	v_cvt_pk_bf16_f32 v152, v34, v35
	v_cvt_pk_bf16_f32 v153, v36, v37
	ds_write_b64 v148, v[152:153] offset:2048
	v_mul_f32_e32 v38, v38, v136
	v_mul_f32_e32 v39, v39, v137
	v_mul_f32_e32 v40, v40, v138
	v_mul_f32_e32 v41, v41, v139
	v_cvt_pk_bf16_f32 v154, v38, v39
	v_cvt_pk_bf16_f32 v155, v40, v41
	ds_write_b64 v148, v[154:155] offset:2064
	v_mul_f32_e32 v42, v42, v140
	v_mul_f32_e32 v43, v43, v141
	v_mul_f32_e32 v44, v44, v142
	v_mul_f32_e32 v45, v45, v143
	v_cvt_pk_bf16_f32 v156, v42, v43
	v_cvt_pk_bf16_f32 v157, v44, v45
	ds_write_b64 v148, v[156:157] offset:2080
	v_mul_f32_e32 v46, v46, v144
	v_mul_f32_e32 v47, v47, v145
	v_mul_f32_e32 v48, v48, v146
	v_mul_f32_e32 v49, v49, v147
	v_cvt_pk_bf16_f32 v158, v46, v47
	v_cvt_pk_bf16_f32 v159, v48, v49
	ds_write_b64 v148, v[158:159] offset:2096
	s_waitcnt lgkmcnt(0)
	ds_read_b64_tr_b16 v[160:161], v149
	ds_read_b64_tr_b16 v[162:163], v149 offset:256
	ds_read_b64_tr_b16 v[164:165], v149 offset:1024
	ds_read_b64_tr_b16 v[166:167], v149 offset:1280
	ds_read_b64_tr_b16 v[168:169], v149 offset:2048
	ds_read_b64_tr_b16 v[170:171], v149 offset:2304
	ds_read_b64_tr_b16 v[172:173], v149 offset:3072
	ds_read_b64_tr_b16 v[174:175], v149 offset:3328
	s_waitcnt lgkmcnt(0)
	global_store_dwordx4 v[150:151], v[160:163], off offset:256
	global_store_dwordx4 v[150:151], v[164:167], off offset:288
	global_store_dwordx4 v[150:151], v[168:171], off offset:320
	global_store_dwordx4 v[150:151], v[172:175], off offset:352
	s_nop 1
	v_mul_f32_e32 v18, v18, v132
	v_mul_f32_e32 v19, v19, v133
	v_mul_f32_e32 v20, v20, v134
	v_mul_f32_e32 v21, v21, v135
	v_cvt_pk_bf16_f32 v152, v18, v19
	v_cvt_pk_bf16_f32 v153, v20, v21
	ds_write_b64 v148, v[152:153]
	v_mul_f32_e32 v22, v22, v136
	v_mul_f32_e32 v23, v23, v137
	v_mul_f32_e32 v24, v24, v138
	v_mul_f32_e32 v25, v25, v139
	v_cvt_pk_bf16_f32 v154, v22, v23
	v_cvt_pk_bf16_f32 v155, v24, v25
	ds_write_b64 v148, v[154:155] offset:16
	v_mul_f32_e32 v26, v26, v140
	v_mul_f32_e32 v27, v27, v141
	v_mul_f32_e32 v28, v28, v142
	v_mul_f32_e32 v29, v29, v143
	v_cvt_pk_bf16_f32 v156, v26, v27
	v_cvt_pk_bf16_f32 v157, v28, v29
	ds_write_b64 v148, v[156:157] offset:32
	v_mul_f32_e32 v30, v30, v144
	v_mul_f32_e32 v31, v31, v145
	v_mul_f32_e32 v32, v32, v146
	v_mul_f32_e32 v33, v33, v147
	v_cvt_pk_bf16_f32 v158, v30, v31
	v_cvt_pk_bf16_f32 v159, v32, v33
	ds_write_b64 v148, v[158:159] offset:48
	v_mul_f32_e32 v2, v2, v132
	v_mul_f32_e32 v3, v3, v133
	v_mul_f32_e32 v4, v4, v134
	v_mul_f32_e32 v5, v5, v135
	v_cvt_pk_bf16_f32 v152, v2, v3
	v_cvt_pk_bf16_f32 v153, v4, v5
	ds_write_b64 v148, v[152:153] offset:2048
	v_mul_f32_e32 v6, v6, v136
	v_mul_f32_e32 v7, v7, v137
	v_mul_f32_e32 v8, v8, v138
	v_mul_f32_e32 v9, v9, v139
	v_cvt_pk_bf16_f32 v154, v6, v7
	v_cvt_pk_bf16_f32 v155, v8, v9
	ds_write_b64 v148, v[154:155] offset:2064
	v_mul_f32_e32 v10, v10, v140
	v_mul_f32_e32 v11, v11, v141
	v_mul_f32_e32 v12, v12, v142
	v_mul_f32_e32 v13, v13, v143
	v_cvt_pk_bf16_f32 v156, v10, v11
	v_cvt_pk_bf16_f32 v157, v12, v13
	ds_write_b64 v148, v[156:157] offset:2080
	v_mul_f32_e32 v14, v14, v144
	v_mul_f32_e32 v15, v15, v145
	v_mul_f32_e32 v16, v16, v146
	v_mul_f32_e32 v17, v17, v147
	v_cvt_pk_bf16_f32 v158, v14, v15
	v_cvt_pk_bf16_f32 v159, v16, v17
	ds_write_b64 v148, v[158:159] offset:2096
	s_waitcnt lgkmcnt(0)
	ds_read_b64_tr_b16 v[160:161], v149
	ds_read_b64_tr_b16 v[162:163], v149 offset:256
	ds_read_b64_tr_b16 v[164:165], v149 offset:1024
	ds_read_b64_tr_b16 v[166:167], v149 offset:1280
	ds_read_b64_tr_b16 v[168:169], v149 offset:2048
	ds_read_b64_tr_b16 v[170:171], v149 offset:2304
	ds_read_b64_tr_b16 v[172:173], v149 offset:3072
	ds_read_b64_tr_b16 v[174:175], v149 offset:3328
	s_waitcnt lgkmcnt(0)
	global_store_dwordx4 v[150:151], v[160:163], off offset:384
	global_store_dwordx4 v[150:151], v[164:167], off offset:416
	global_store_dwordx4 v[150:151], v[168:171], off offset:448
	global_store_dwordx4 v[150:151], v[172:175], off offset:480
	s_nop 1
	s_add_i32 s8, s8, s96
	s_add_i32 s11, s11, s33
	s_cmpk_lt_i32 s8, 0x800
	s_cbranch_scc0 .LBB0_1950
